# aligned combo12 + all validated micro-edits stacked (LDS base register, UP epilogue address/broadcast trim, permlane reductions, phase-start trims)
# speedup vs baseline: 1.0078x; 1.0059x over previous
; template <class Epi, class Sched, bool ALIGN_EPI = false, bool SP2 = false, bool ACHUNK = false>
; __device__ __forceinline__ void gemm_phase(PG8_LAS unsigned char* lds, const Gemm g, const Sched& S, const Epi& E) {
;     ...
;         const bool has_next = S.next(ui + 1, nxt);
;         const char* nA = has_next ? (const char*)g.A + (size_t)nxt.pm * tstepA : cA; const char* nB = has_next ? (const char*)g.Bt + (size_t)nxt.pn * tstepB : cB;
;         for (int t = 0; t < nt; t += 2) {
;             const bool last = (t == nt - 2);
;             if constexpr (Epi::HAS_MID) { if (t == Epi::MID_T) E.mid(acc, cur, wr, wc, fr, fq, ShflDev{}); }
;     ...
;         if (!has_next) break;
;         if constexpr (Epi::HAS_INIT) E.init(acc, nxt, wr, wc, fr, fq);
;         else {
; #pragma unroll
;         for (int a = 0; a < 2; ++a)
; #pragma unroll
;             for (int b = 0; b < 2; ++b)
; #pragma unroll
;                 for (int m = 0; m < 4; ++m)
; #pragma unroll
;                     for (int n = 0; n < 2; ++n) acc[a][b][m][n] = (f32x4){0.f, 0.f, 0.f, 0.f};
;         }
;         cur = nxt; cA = nA; cB = nB; ++ui;
.LBB0_264:
	s_nop 0
	s_andn2_b64 vcc, exec, s[30:31]
	s_cbranch_vccnz .Lmg_zero_stub
	s_lshl_b32 s8, s46, 8
	s_lshl_b32 s48, s45, 8
	s_or_b32 s47, s8, s25
	s_add_i32 s48, s48, s24
	s_add_u32 s49, s6, 0x100
	s_addc_u32 s50, s7, 0
	s_add_u32 s6, s4, 0x80
	v_mov_b32_e32 v4, v3
	v_mov_b32_e32 v5, v3
	s_addc_u32 s7, s5, 0
	v_mov_b32_e32 v2, v3
	v_mov_b64_e32 v[8:9], v[4:5]
	v_mov_b64_e32 v[12:13], v[4:5]
	v_mov_b64_e32 v[24:25], v[4:5]
	v_mov_b64_e32 v[28:29], v[4:5]
	v_mov_b64_e32 v[40:41], v[4:5]
	v_mov_b64_e32 v[44:45], v[4:5]
	v_mov_b64_e32 v[56:57], v[4:5]
	v_mov_b64_e32 v[60:61], v[4:5]
	v_mov_b64_e32 v[16:17], v[4:5]
	v_mov_b64_e32 v[20:21], v[4:5]
	v_mov_b64_e32 v[32:33], v[4:5]
	v_mov_b64_e32 v[36:37], v[4:5]
	v_mov_b64_e32 v[48:49], v[4:5]
	v_mov_b64_e32 v[52:53], v[4:5]
	v_mov_b64_e32 v[64:65], v[4:5]
	v_mov_b64_e32 v[68:69], v[4:5]
	v_mov_b64_e32 v[72:73], v[4:5]
	v_mov_b64_e32 v[76:77], v[4:5]
	v_mov_b64_e32 v[88:89], v[4:5]
	v_mov_b64_e32 v[92:93], v[4:5]
	v_mov_b64_e32 v[104:105], v[4:5]
	v_mov_b64_e32 v[108:109], v[4:5]
	v_mov_b64_e32 v[120:121], v[4:5]
	v_mov_b64_e32 v[124:125], v[4:5]
	v_mov_b64_e32 v[80:81], v[4:5]
	v_mov_b64_e32 v[84:85], v[4:5]
	v_mov_b64_e32 v[96:97], v[4:5]
	v_mov_b64_e32 v[100:101], v[4:5]
	v_mov_b64_e32 v[112:113], v[4:5]
	v_mov_b64_e32 v[116:117], v[4:5]
	v_mov_b64_e32 v[132:133], v[4:5]
	v_mov_b64_e32 v[128:129], v[4:5]
	v_lshl_add_u64 v[210:211], s[6:7], 0, v[206:207]
	v_lshl_add_u64 v[212:213], s[6:7], 0, v[208:209]
	s_mov_b32 s8, 0
	s_mov_b64 s[6:7], 0
	v_mov_b64_e32 v[6:7], v[2:3]
	v_mov_b64_e32 v[10:11], v[2:3]
	v_mov_b64_e32 v[22:23], v[2:3]
	v_mov_b64_e32 v[26:27], v[2:3]
	v_mov_b64_e32 v[38:39], v[2:3]
	v_mov_b64_e32 v[42:43], v[2:3]
	v_mov_b64_e32 v[54:55], v[2:3]
	v_mov_b64_e32 v[58:59], v[2:3]
	v_mov_b64_e32 v[14:15], v[2:3]
	v_mov_b64_e32 v[18:19], v[2:3]
	v_mov_b64_e32 v[30:31], v[2:3]
	v_mov_b64_e32 v[34:35], v[2:3]
	v_mov_b64_e32 v[46:47], v[2:3]
	v_mov_b64_e32 v[50:51], v[2:3]
	v_mov_b64_e32 v[62:63], v[2:3]
	v_mov_b64_e32 v[66:67], v[2:3]
	v_mov_b64_e32 v[70:71], v[2:3]
	v_mov_b64_e32 v[74:75], v[2:3]
	v_mov_b64_e32 v[86:87], v[2:3]
	v_mov_b64_e32 v[90:91], v[2:3]
	v_mov_b64_e32 v[102:103], v[2:3]
	v_mov_b64_e32 v[106:107], v[2:3]
	v_mov_b64_e32 v[118:119], v[2:3]
	v_mov_b64_e32 v[122:123], v[2:3]
	v_mov_b64_e32 v[78:79], v[2:3]
	v_mov_b64_e32 v[82:83], v[2:3]
	v_mov_b64_e32 v[94:95], v[2:3]
	v_mov_b64_e32 v[98:99], v[2:3]
	v_mov_b64_e32 v[110:111], v[2:3]
	v_mov_b64_e32 v[114:115], v[2:3]
	v_mov_b64_e32 v[130:131], v[2:3]
	v_mov_b64_e32 v[126:127], v[2:3]
	v_add_u32_e32 v218, 0x10000, v235
	s_cmp_lg_u32 s8, 8
	s_cbranch_scc1 .LBB0_268
	s_branch .LBB0_267
